# nt hint on one-touch f32 weight loads of the conversion passes (conv_win_dyn, conv_ffn, conv_mixer)
# baseline (speedup 1.0000x reference)
.LBB0_1939:
	v_cmp_gt_i32_e32 vcc, 0, v64
	s_and_saveexec_b64 s[22:23], vcc
	s_xor_b64 s[22:23], exec, s[22:23]
	s_or_saveexec_b64 s[24:25], s[22:23]
	s_lshl_b32 s22, s21, 6
	v_or_b32_e32 v100, s22, v104
	v_mov_b32_e32 v68, 0
	v_lshlrev_b64 v[102:103], 2, v[64:65]
	v_mov_b32_e32 v69, 0
	v_mov_b32_e32 v70, 0
	v_mov_b32_e32 v71, 0
	v_mov_b32_e32 v72, 0
	v_mov_b32_e32 v73, 0
	v_mov_b32_e32 v74, 0
	v_mov_b32_e32 v75, 0
	s_xor_b64 exec, exec, s[24:25]
	s_cbranch_execz .LBB0_1941
	v_or_b32_e32 v64, 8, v100
	v_mad_i64_i32 v[66:67], s[28:29], s20, v100, 0
	v_mad_i64_i32 v[68:69], s[28:29], s20, v64, 0
	v_lshl_add_u64 v[66:67], v[66:67], 2, s[18:19]
	v_lshl_add_u64 v[68:69], v[68:69], 2, s[18:19]
	v_lshl_add_u64 v[66:67], v[66:67], 0, v[102:103]
	v_lshl_add_u64 v[72:73], v[68:69], 0, v[102:103]
	global_load_dwordx4 v[68:71], v[66:67], off nt
	s_nop 0
	global_load_dwordx4 v[72:75], v[72:73], off nt
.LBB0_1941:
	s_or_b64 exec, exec, s[24:25]
	s_and_saveexec_b64 s[24:25], vcc
	s_xor_b64 s[24:25], exec, s[24:25]
	s_or_saveexec_b64 s[24:25], s[24:25]
	v_mov_b32_e32 v76, 0
	v_mov_b32_e32 v77, 0
	v_mov_b32_e32 v78, 0
	v_mov_b32_e32 v79, 0
	v_mov_b32_e32 v80, 0
	v_mov_b32_e32 v81, 0
	v_mov_b32_e32 v82, 0
	v_mov_b32_e32 v83, 0
	s_xor_b64 exec, exec, s[24:25]
	s_cbranch_execz .LBB0_1943
	v_or_b32_e32 v64, 16, v100
	v_mad_i64_i32 v[66:67], s[28:29], s20, v64, 0
	v_or_b32_e32 v64, 24, v100
	v_mad_i64_i32 v[76:77], s[28:29], s20, v64, 0
	v_lshl_add_u64 v[66:67], v[66:67], 2, s[18:19]
	v_lshl_add_u64 v[76:77], v[76:77], 2, s[18:19]
	v_lshl_add_u64 v[66:67], v[66:67], 0, v[102:103]
	v_lshl_add_u64 v[80:81], v[76:77], 0, v[102:103]
	global_load_dwordx4 v[76:79], v[66:67], off nt
	s_nop 0
	global_load_dwordx4 v[80:83], v[80:81], off nt
.LBB0_1943:
	s_or_b64 exec, exec, s[24:25]
	s_and_saveexec_b64 s[24:25], vcc
	s_xor_b64 s[24:25], exec, s[24:25]
	s_or_saveexec_b64 s[24:25], s[24:25]
	v_mov_b32_e32 v88, 0
	v_mov_b32_e32 v89, 0
	v_mov_b32_e32 v90, 0
	v_mov_b32_e32 v91, 0
	v_mov_b32_e32 v84, 0
	v_mov_b32_e32 v85, 0
	v_mov_b32_e32 v86, 0
	v_mov_b32_e32 v87, 0
	s_xor_b64 exec, exec, s[24:25]
	s_cbranch_execz .LBB0_1945
	v_or_b32_e32 v64, 32, v100
	v_mad_i64_i32 v[66:67], s[28:29], s20, v64, 0
	v_or_b32_e32 v64, 40, v100
	v_mad_i64_i32 v[84:85], s[28:29], s20, v64, 0
	v_lshl_add_u64 v[66:67], v[66:67], 2, s[18:19]
	v_lshl_add_u64 v[84:85], v[84:85], 2, s[18:19]
	v_lshl_add_u64 v[66:67], v[66:67], 0, v[102:103]
	v_lshl_add_u64 v[84:85], v[84:85], 0, v[102:103]
	global_load_dwordx4 v[88:91], v[66:67], off nt
	s_nop 0
	global_load_dwordx4 v[84:87], v[84:85], off nt
.LBB0_1945:
	s_or_b64 exec, exec, s[24:25]
	s_and_saveexec_b64 s[24:25], vcc
	s_xor_b64 s[24:25], exec, s[24:25]
	s_or_saveexec_b64 s[24:25], s[24:25]
	v_mov_b32_e32 v66, v65
	v_mov_b32_e32 v67, v65
	v_mov_b32_e32 v64, v65
	v_mov_b64_e32 v[98:99], v[66:67]
	v_mov_b32_e32 v92, 0
	v_mov_b64_e32 v[96:97], v[64:65]
	v_mov_b32_e32 v93, 0
	v_mov_b32_e32 v94, 0
	v_mov_b32_e32 v95, 0
	s_xor_b64 exec, exec, s[24:25]
	s_cbranch_execz .LBB0_1949
	v_or_b32_e32 v64, 48, v100
	v_mad_i64_i32 v[66:67], s[28:29], s20, v64, 0
	v_or_b32_e32 v64, 56, v100
	v_mad_i64_i32 v[92:93], s[20:21], s20, v64, 0
	v_lshl_add_u64 v[66:67], v[66:67], 2, s[18:19]
	v_lshl_add_u64 v[92:93], v[92:93], 2, s[18:19]
	v_lshl_add_u64 v[66:67], v[66:67], 0, v[102:103]
	v_lshl_add_u64 v[96:97], v[92:93], 0, v[102:103]
	global_load_dwordx4 v[92:95], v[66:67], off nt
	s_nop 0
	global_load_dwordx4 v[96:99], v[96:97], off nt

.LBB0_1960:
.LBB0_1961:
	s_or_saveexec_b64 s[18:19], s[18:19]
	s_load_dwordx2 s[20:21], s[0:1], 0x38
	s_xor_b64 exec, exec, s[18:19]
	v_add_u32_e32 v64, 0x800, v0
	s_or_b64 exec, exec, s[18:19]
	v_mov_b32_e32 v2, v65
	v_mov_b32_e32 v3, v65
	s_waitcnt lgkmcnt(0)
	s_add_u32 s18, s20, 0x2440000
	v_mov_b32_e32 v0, v65
	v_mov_b32_e32 v1, v65
	v_mov_b64_e32 v[10:11], v[2:3]
	s_addc_u32 s19, s21, 0
	v_cmp_lt_i32_e32 vcc, -1, v64
	v_lshl_or_b32 v66, s23, 6, v104
	v_mov_b32_e32 v16, 0
	v_mov_b64_e32 v[8:9], v[0:1]
	v_mov_b32_e32 v20, 0
	v_mov_b32_e32 v21, 0
	v_mov_b32_e32 v22, 0
	v_mov_b32_e32 v23, 0
	s_and_saveexec_b64 s[20:21], vcc
	s_cbranch_execz .LBB0_1965
	v_mov_b64_e32 v[8:9], s[18:19]
	v_or_b32_e32 v17, 8, v66
	v_mad_i64_i32 v[10:11], s[24:25], v66, s75, v[8:9]
	v_lshlrev_b64 v[18:19], 2, v[64:65]
	v_mad_i64_i32 v[8:9], s[24:25], v17, s75, v[8:9]
	v_lshl_add_u64 v[10:11], v[10:11], 0, v[18:19]
	v_lshl_add_u64 v[8:9], v[8:9], 0, v[18:19]
	global_load_dwordx4 v[20:23], v[10:11], off nt
	s_nop 0
	global_load_dwordx4 v[8:11], v[8:9], off nt
.LBB0_1965:
	s_or_b64 exec, exec, s[20:21]
	v_mov_b32_e32 v17, 0
	v_mov_b32_e32 v18, 0
	v_mov_b32_e32 v19, 0
	s_and_saveexec_b64 s[20:21], vcc
	s_cbranch_execz .LBB0_1967
	v_or_b32_e32 v2, 16, v66
	v_mov_b64_e32 v[0:1], s[18:19]
	v_or_b32_e32 v18, 24, v66
	v_mad_i64_i32 v[2:3], s[24:25], v2, s75, v[0:1]
	v_lshlrev_b64 v[16:17], 2, v[64:65]
	v_mad_i64_i32 v[0:1], s[24:25], v18, s75, v[0:1]
	v_lshl_add_u64 v[2:3], v[2:3], 0, v[16:17]
	v_lshl_add_u64 v[0:1], v[0:1], 0, v[16:17]
	global_load_dwordx4 v[16:19], v[2:3], off nt
	s_nop 0
	global_load_dwordx4 v[0:3], v[0:1], off nt
.LBB0_1967:
	s_or_b64 exec, exec, s[20:21]
	v_mov_b32_e32 v32, v65
	v_mov_b32_e32 v33, v65
	v_mov_b32_e32 v34, v65
	v_mov_b32_e32 v35, v65
	v_mov_b32_e32 v43, 0
	v_mov_b32_e32 v44, 0
	v_mov_b32_e32 v45, 0
	v_mov_b32_e32 v46, 0
	v_mov_b32_e32 v47, 0
	s_and_saveexec_b64 s[20:21], vcc
	s_cbranch_execz .LBB0_1969
	v_or_b32_e32 v34, 32, v66
	v_mov_b64_e32 v[32:33], s[18:19]
	v_or_b32_e32 v42, 40, v66
	v_mad_i64_i32 v[34:35], s[24:25], v34, s75, v[32:33]
	v_lshlrev_b64 v[40:41], 2, v[64:65]
	v_mad_i64_i32 v[32:33], s[24:25], v42, s75, v[32:33]
	v_lshl_add_u64 v[34:35], v[34:35], 0, v[40:41]
	v_lshl_add_u64 v[32:33], v[32:33], 0, v[40:41]
	global_load_dwordx4 v[44:47], v[34:35], off nt
	s_nop 0
	global_load_dwordx4 v[32:35], v[32:33], off nt
.LBB0_1969:
	s_or_b64 exec, exec, s[20:21]
	v_mov_b32_e32 v42, 0
	v_mov_b32_e32 v41, 0
	v_mov_b32_e32 v40, 0
	v_mov_b32_e32 v59, 0
	v_mov_b32_e32 v58, 0
	v_mov_b32_e32 v57, 0
	v_mov_b32_e32 v56, 0
	s_and_saveexec_b64 s[20:21], vcc
	s_cbranch_execz .LBB0_1971
	v_or_b32_e32 v42, 48, v66
	v_mov_b64_e32 v[40:41], s[18:19]
	v_or_b32_e32 v58, 56, v66
	v_mad_i64_i32 v[42:43], s[18:19], v42, s75, v[40:41]
	v_lshlrev_b64 v[56:57], 2, v[64:65]
	v_mad_i64_i32 v[40:41], s[18:19], v58, s75, v[40:41]
	v_lshl_add_u64 v[42:43], v[42:43], 0, v[56:57]
	v_lshl_add_u64 v[40:41], v[40:41], 0, v[56:57]
	global_load_dwordx4 v[56:59], v[42:43], off nt
	s_nop 0
	global_load_dwordx4 v[40:43], v[40:41], off nt

.LBB0_1984:
.LBB0_1985:
	s_or_saveexec_b64 s[18:19], s[18:19]
	s_load_dwordx2 s[26:27], s[0:1], 0x38
	s_xor_b64 exec, exec, s[18:19]
	v_add_u32_e32 v64, 0x800, v4
	s_or_b64 exec, exec, s[18:19]
	v_mov_b32_e32 v6, v65
	v_mov_b32_e32 v7, v65
	s_waitcnt lgkmcnt(0)
	s_add_u32 s18, s26, 0x2440000
	v_mov_b32_e32 v4, v65
	v_mov_b32_e32 v5, v65
	v_mov_b64_e32 v[14:15], v[6:7]
	s_addc_u32 s19, s27, 0
	v_cmp_lt_i32_e32 vcc, -1, v64
	v_lshl_or_b32 v66, s23, 6, v104
	v_mov_b32_e32 v28, 0
	v_mov_b64_e32 v[12:13], v[4:5]
	v_mov_b32_e32 v24, 0
	v_mov_b32_e32 v25, 0
	v_mov_b32_e32 v26, 0
	v_mov_b32_e32 v27, 0
	s_and_saveexec_b64 s[26:27], vcc
	s_cbranch_execz .LBB0_1989
	v_mov_b64_e32 v[12:13], s[18:19]
	v_or_b32_e32 v26, 8, v66
	v_mad_i64_i32 v[14:15], s[28:29], v66, s75, v[12:13]
	v_lshlrev_b64 v[24:25], 2, v[64:65]
	v_mad_i64_i32 v[12:13], s[28:29], v26, s75, v[12:13]
	v_lshl_add_u64 v[14:15], v[14:15], 0, v[24:25]
	v_lshl_add_u64 v[12:13], v[12:13], 0, v[24:25]
	global_load_dwordx4 v[24:27], v[14:15], off nt
	s_nop 0
	global_load_dwordx4 v[12:15], v[12:13], off nt
.LBB0_1989:
	s_or_b64 exec, exec, s[26:27]
	v_mov_b32_e32 v29, 0
	v_mov_b32_e32 v30, 0
	v_mov_b32_e32 v31, 0
	s_and_saveexec_b64 s[26:27], vcc
	s_cbranch_execz .LBB0_1991
	v_or_b32_e32 v6, 16, v66
	v_mov_b64_e32 v[4:5], s[18:19]
	v_or_b32_e32 v30, 24, v66
	v_mad_i64_i32 v[6:7], s[28:29], v6, s75, v[4:5]
	v_lshlrev_b64 v[28:29], 2, v[64:65]
	v_mad_i64_i32 v[4:5], s[28:29], v30, s75, v[4:5]
	v_lshl_add_u64 v[6:7], v[6:7], 0, v[28:29]
	v_lshl_add_u64 v[4:5], v[4:5], 0, v[28:29]
	global_load_dwordx4 v[28:31], v[6:7], off nt
	s_nop 0
	global_load_dwordx4 v[4:7], v[4:5], off nt
.LBB0_1991:
	s_or_b64 exec, exec, s[26:27]
	v_mov_b32_e32 v36, v65
	v_mov_b32_e32 v37, v65
	v_mov_b32_e32 v38, v65
	v_mov_b32_e32 v39, v65
	v_mov_b32_e32 v51, 0
	v_mov_b32_e32 v52, 0
	v_mov_b32_e32 v53, 0
	v_mov_b32_e32 v54, 0
	v_mov_b32_e32 v55, 0
	s_and_saveexec_b64 s[26:27], vcc
	s_cbranch_execz .LBB0_1993
	v_or_b32_e32 v38, 32, v66
	v_mov_b64_e32 v[36:37], s[18:19]
	v_or_b32_e32 v50, 40, v66
	v_mad_i64_i32 v[38:39], s[28:29], v38, s75, v[36:37]
	v_lshlrev_b64 v[48:49], 2, v[64:65]
	v_mad_i64_i32 v[36:37], s[28:29], v50, s75, v[36:37]
	v_lshl_add_u64 v[38:39], v[38:39], 0, v[48:49]
	v_lshl_add_u64 v[36:37], v[36:37], 0, v[48:49]
	global_load_dwordx4 v[52:55], v[38:39], off nt
	s_nop 0
	global_load_dwordx4 v[36:39], v[36:37], off nt
.LBB0_1993:
	s_or_b64 exec, exec, s[26:27]
	v_mov_b32_e32 v50, 0
	v_mov_b32_e32 v49, 0
	v_mov_b32_e32 v48, 0
	v_mov_b32_e32 v63, 0
	v_mov_b32_e32 v62, 0
	v_mov_b32_e32 v61, 0
	v_mov_b32_e32 v60, 0
	s_and_saveexec_b64 s[26:27], vcc
	s_cbranch_execz .LBB0_1995
	v_or_b32_e32 v50, 48, v66
	v_mov_b64_e32 v[48:49], s[18:19]
	v_or_b32_e32 v62, 56, v66
	v_mad_i64_i32 v[50:51], s[18:19], v50, s75, v[48:49]
	v_lshlrev_b64 v[60:61], 2, v[64:65]
	v_mad_i64_i32 v[48:49], s[18:19], v62, s75, v[48:49]
	v_lshl_add_u64 v[50:51], v[50:51], 0, v[60:61]
	v_lshl_add_u64 v[48:49], v[48:49], 0, v[60:61]
	global_load_dwordx4 v[60:63], v[50:51], off nt
	s_nop 0
	global_load_dwordx4 v[48:51], v[48:49], off nt

.LBB0_2174:
	s_lshr_b32 s19, s36, 5
	v_cvt_f32_ubyte0_e32 v64, s19
	v_rcp_iflag_f32_e32 v64, v64
	s_sub_i32 s22, 0, s19
	s_abs_i32 s21, s27
	s_ashr_i32 s18, s27, 31
	v_mul_f32_e32 v64, 0x4f7ffffe, v64
	v_cvt_u32_f32_e32 v64, v64
	s_nop 0
	v_readfirstlane_b32 s23, v64
	s_mul_i32 s22, s22, s23
	s_mul_hi_u32 s22, s23, s22
	s_add_i32 s23, s23, s22
	s_mul_hi_u32 s22, s21, s23
	s_mul_i32 s23, s22, s19
	s_sub_i32 s21, s21, s23
	s_add_i32 s24, s22, 1
	s_sub_i32 s23, s21, s19
	s_cmp_ge_u32 s21, s19
	s_cselect_b32 s22, s24, s22
	s_cselect_b32 s21, s23, s21
	s_add_i32 s23, s22, 1
	s_cmp_ge_u32 s21, s19
	s_cselect_b32 s21, s23, s22
	s_xor_b32 s21, s21, s18
	s_sub_i32 s18, s21, s18
	s_mul_i32 s19, s18, s19
	s_sub_i32 s19, s27, s19
	s_lshl_b32 s21, s19, 4
	s_lshl_b32 s38, s19, 5
	s_and_b32 s21, s21, 0xffffff80
	v_and_or_b32 v66, s19, 4, v104
	v_or_b32_e32 v64, s38, v103
	v_add_u32_e32 v66, s21, v66
	v_and_or_b32 v66, v64, s49, v66
	v_cndmask_b32_e64 v64, v64, v66, s[6:7]
	v_cmp_gt_i32_e32 vcc, 0, v64
	s_and_saveexec_b64 s[6:7], vcc
	s_xor_b64 s[6:7], exec, s[6:7]
	s_or_saveexec_b64 s[6:7], s[6:7]
	s_lshl_b32 s18, s18, 6
	v_or_b32_e32 v99, s18, v102
	v_mov_b32_e32 v66, 0
	v_mov_b32_e32 v67, 0
	v_mov_b32_e32 v68, 0
	v_mov_b32_e32 v69, 0
	v_mov_b32_e32 v70, 0
	v_mov_b32_e32 v71, 0
	v_mov_b32_e32 v72, 0
	v_mov_b32_e32 v73, 0
	s_xor_b64 exec, exec, s[6:7]
	s_cbranch_execz .LBB0_2176
	v_or_b32_e32 v70, 8, v99
	v_mad_i64_i32 v[66:67], s[22:23], s20, v99, 0
	v_mad_i64_i32 v[70:71], s[22:23], s20, v70, 0
	v_lshl_add_u64 v[66:67], v[66:67], 2, s[16:17]
	v_lshlrev_b64 v[68:69], 2, v[64:65]
	v_lshl_add_u64 v[70:71], v[70:71], 2, s[16:17]
	v_lshl_add_u64 v[66:67], v[66:67], 0, v[68:69]
	v_lshl_add_u64 v[70:71], v[70:71], 0, v[68:69]
	global_load_dwordx4 v[66:69], v[66:67], off nt
	s_nop 0
	global_load_dwordx4 v[70:73], v[70:71], off nt
.LBB0_2176:
	s_or_b64 exec, exec, s[6:7]
	s_and_saveexec_b64 s[6:7], vcc
	s_xor_b64 s[6:7], exec, s[6:7]
	s_or_saveexec_b64 s[6:7], s[6:7]
	v_mov_b32_e32 v74, 0
	v_mov_b32_e32 v75, 0
	v_mov_b32_e32 v76, 0
	v_mov_b32_e32 v77, 0
	v_mov_b32_e32 v78, 0
	v_mov_b32_e32 v79, 0
	v_mov_b32_e32 v80, 0
	v_mov_b32_e32 v81, 0
	s_xor_b64 exec, exec, s[6:7]
	s_cbranch_execz .LBB0_2178
	v_or_b32_e32 v74, 16, v99
	v_or_b32_e32 v78, 24, v99
	v_mad_i64_i32 v[74:75], s[22:23], s20, v74, 0
	v_mad_i64_i32 v[78:79], s[22:23], s20, v78, 0
	v_lshl_add_u64 v[74:75], v[74:75], 2, s[16:17]
	v_lshlrev_b64 v[76:77], 2, v[64:65]
	v_lshl_add_u64 v[78:79], v[78:79], 2, s[16:17]
	v_lshl_add_u64 v[74:75], v[74:75], 0, v[76:77]
	v_lshl_add_u64 v[78:79], v[78:79], 0, v[76:77]
	global_load_dwordx4 v[74:77], v[74:75], off nt
	s_nop 0
	global_load_dwordx4 v[78:81], v[78:79], off nt
.LBB0_2178:
	s_or_b64 exec, exec, s[6:7]
	s_and_saveexec_b64 s[6:7], vcc
	s_xor_b64 s[6:7], exec, s[6:7]
	s_or_saveexec_b64 s[6:7], s[6:7]
	v_mov_b32_e32 v82, 0
	v_mov_b32_e32 v83, 0
	v_mov_b32_e32 v84, 0
	v_mov_b32_e32 v85, 0
	v_mov_b32_e32 v86, 0
	v_mov_b32_e32 v87, 0
	v_mov_b32_e32 v88, 0
	v_mov_b32_e32 v89, 0
	s_xor_b64 exec, exec, s[6:7]
	s_cbranch_execz .LBB0_2180
	v_or_b32_e32 v82, 32, v99
	v_or_b32_e32 v86, 40, v99
	v_mad_i64_i32 v[82:83], s[22:23], s20, v82, 0
	v_mad_i64_i32 v[86:87], s[22:23], s20, v86, 0
	v_lshl_add_u64 v[82:83], v[82:83], 2, s[16:17]
	v_lshlrev_b64 v[84:85], 2, v[64:65]
	v_lshl_add_u64 v[86:87], v[86:87], 2, s[16:17]
	v_lshl_add_u64 v[82:83], v[82:83], 0, v[84:85]
	v_lshl_add_u64 v[86:87], v[86:87], 0, v[84:85]
	global_load_dwordx4 v[82:85], v[82:83], off nt
	s_nop 0
	global_load_dwordx4 v[86:89], v[86:87], off nt
.LBB0_2180:
	s_or_b64 exec, exec, s[6:7]
	s_and_saveexec_b64 s[6:7], vcc
	s_xor_b64 s[6:7], exec, s[6:7]
	s_or_saveexec_b64 s[6:7], s[6:7]
	v_mov_b32_e32 v90, 0
	v_mov_b32_e32 v91, 0
	v_mov_b32_e32 v92, 0
	v_mov_b32_e32 v93, 0
	v_mov_b32_e32 v94, 0
	v_mov_b32_e32 v95, 0
	v_mov_b32_e32 v96, 0
	v_mov_b32_e32 v97, 0
	s_xor_b64 exec, exec, s[6:7]
	s_cbranch_execz .LBB0_2184
	v_or_b32_e32 v90, 48, v99
	v_lshlrev_b64 v[92:93], 2, v[64:65]
	v_or_b32_e32 v64, 56, v99
	v_mad_i64_i32 v[90:91], s[22:23], s20, v90, 0
	v_mad_i64_i32 v[94:95], s[20:21], s20, v64, 0
	v_lshl_add_u64 v[90:91], v[90:91], 2, s[16:17]
	v_lshl_add_u64 v[94:95], v[94:95], 2, s[16:17]
	v_lshl_add_u64 v[90:91], v[90:91], 0, v[92:93]
	v_lshl_add_u64 v[94:95], v[94:95], 0, v[92:93]
	global_load_dwordx4 v[90:93], v[90:91], off nt
	s_nop 0
	global_load_dwordx4 v[94:97], v[94:95], off nt

.LBB0_2191:
	s_lshr_b32 s25, s41, 5
	v_cvt_f32_ubyte0_e32 v0, s25
	v_rcp_iflag_f32_e32 v0, v0
	s_sub_i32 s34, 0, s25
	s_abs_i32 s29, s40
	s_ashr_i32 s28, s40, 31
	v_mul_f32_e32 v0, 0x4f7ffffe, v0
	v_cvt_u32_f32_e32 v0, v0
	v_mov_b32_e32 v4, 0
	v_mov_b32_e32 v5, 0
	v_mov_b32_e32 v6, 0
	v_readfirstlane_b32 s35, v0
	s_mul_i32 s34, s34, s35
	s_mul_hi_u32 s34, s35, s34
	s_add_i32 s35, s35, s34
	s_mul_hi_u32 s34, s29, s35
	s_mul_i32 s35, s34, s25
	s_sub_i32 s29, s29, s35
	s_add_i32 s43, s34, 1
	s_sub_i32 s35, s29, s25
	s_cmp_ge_u32 s29, s25
	s_cselect_b32 s34, s43, s34
	s_cselect_b32 s29, s35, s29
	s_add_i32 s35, s34, 1
	s_cmp_ge_u32 s29, s25
	s_cselect_b32 s29, s35, s34
	s_xor_b32 s29, s29, s28
	s_sub_i32 s28, s29, s28
	s_mul_i32 s25, s28, s25
	s_sub_i32 s25, s40, s25
	s_lshl_b32 s29, s25, 4
	s_and_b32 s29, s29, 0xffffff80
	v_and_or_b32 v1, s25, 4, v104
	v_lshl_or_b32 v0, s25, 5, v103
	v_add_u32_e32 v1, s29, v1
	v_and_or_b32 v1, v0, s49, v1
	v_cndmask_b32_e64 v64, v0, v1, s[6:7]
	v_cmp_lt_i32_e32 vcc, -1, v64
	v_lshl_or_b32 v99, s28, 6, v102
	v_mov_b32_e32 v0, 0
	v_lshlrev_b64 v[100:101], 2, v[64:65]
	v_mov_b32_e32 v7, 0
	s_nop 0
	v_mov_b32_e32 v8, 0
	v_mov_b32_e32 v9, 0
	v_mov_b32_e32 v10, 0
	v_mov_b32_e32 v11, 0
	s_and_saveexec_b64 s[6:7], vcc
	s_cbranch_execz .LBB0_2193
	v_or_b32_e32 v1, 8, v99
	v_mad_i64_i32 v[2:3], s[28:29], s24, v99, 0
	v_mad_i64_i32 v[4:5], s[28:29], s24, v1, 0
	v_lshl_add_u64 v[2:3], v[2:3], 2, s[20:21]
	v_lshl_add_u64 v[4:5], v[4:5], 2, s[20:21]
	v_lshl_add_u64 v[2:3], v[2:3], 0, v[100:101]
	v_lshl_add_u64 v[8:9], v[4:5], 0, v[100:101]
	global_load_dwordx4 v[4:7], v[2:3], off nt
	s_nop 0
	global_load_dwordx4 v[8:11], v[8:9], off nt
.LBB0_2193:
	s_or_b64 exec, exec, s[6:7]
	v_mov_b32_e32 v1, 0
	v_mov_b32_e32 v2, 0
	v_mov_b32_e32 v3, 0
	v_mov_b32_e32 v24, 0
	v_mov_b32_e32 v25, 0
	v_mov_b32_e32 v26, 0
	v_mov_b32_e32 v27, 0
	s_and_saveexec_b64 s[6:7], vcc
	s_cbranch_execz .LBB0_2195
	v_or_b32_e32 v0, 16, v99
	v_or_b32_e32 v2, 24, v99
	v_mad_i64_i32 v[0:1], s[28:29], s24, v0, 0
	v_mad_i64_i32 v[2:3], s[28:29], s24, v2, 0
	v_lshl_add_u64 v[0:1], v[0:1], 2, s[20:21]
	v_lshl_add_u64 v[2:3], v[2:3], 2, s[20:21]
	v_lshl_add_u64 v[0:1], v[0:1], 0, v[100:101]
	v_lshl_add_u64 v[24:25], v[2:3], 0, v[100:101]
	global_load_dwordx4 v[0:3], v[0:1], off nt
	s_nop 0
	global_load_dwordx4 v[24:27], v[24:25], off nt
.LBB0_2195:
	s_or_b64 exec, exec, s[6:7]
	s_nop 0
	v_mov_b32_e32 v31, 0
	v_mov_b32_e32 v36, 0
	v_mov_b32_e32 v37, 0
	v_mov_b32_e32 v38, 0
	v_mov_b32_e32 v39, 0
	v_mov_b32_e32 v40, 0
	v_mov_b32_e32 v41, 0
	v_mov_b32_e32 v42, 0
	v_mov_b32_e32 v43, 0
	s_and_saveexec_b64 s[6:7], vcc
	s_cbranch_execz .LBB0_2197
	v_or_b32_e32 v28, 32, v99
	v_or_b32_e32 v30, 40, v99
	v_mad_i64_i32 v[28:29], s[28:29], s24, v28, 0
	v_mad_i64_i32 v[36:37], s[28:29], s24, v30, 0
	v_lshl_add_u64 v[28:29], v[28:29], 2, s[20:21]
	v_lshl_add_u64 v[36:37], v[36:37], 2, s[20:21]
	v_lshl_add_u64 v[28:29], v[28:29], 0, v[100:101]
	v_lshl_add_u64 v[40:41], v[36:37], 0, v[100:101]
	global_load_dwordx4 v[36:39], v[28:29], off nt
	s_nop 0
	global_load_dwordx4 v[40:43], v[40:41], off nt
.LBB0_2197:
	s_or_b64 exec, exec, s[6:7]
	v_mov_b32_e32 v30, 0
	v_mov_b32_e32 v29, 0
	v_mov_b32_e32 v28, 0
	v_mov_b32_e32 v59, 0
	v_mov_b32_e32 v58, 0
	v_mov_b32_e32 v57, 0
	v_mov_b32_e32 v56, 0
	s_and_saveexec_b64 s[6:7], vcc
	s_cbranch_execz .LBB0_2199
	v_or_b32_e32 v28, 48, v99
	v_or_b32_e32 v30, 56, v99
	v_mad_i64_i32 v[28:29], s[28:29], s24, v28, 0
	v_mad_i64_i32 v[30:31], s[24:25], s24, v30, 0
	v_lshl_add_u64 v[28:29], v[28:29], 2, s[20:21]
	v_lshl_add_u64 v[30:31], v[30:31], 2, s[20:21]
	v_lshl_add_u64 v[28:29], v[28:29], 0, v[100:101]
	v_lshl_add_u64 v[30:31], v[30:31], 0, v[100:101]
	global_load_dwordx4 v[56:59], v[28:29], off nt
	s_nop 0
	global_load_dwordx4 v[28:31], v[30:31], off nt

.LBB0_2207:
	s_lshr_b32 s19, s36, 5
	s_nop 0
	v_cvt_f32_ubyte0_e32 v12, s19
	v_rcp_iflag_f32_e32 v12, v12
	s_sub_i32 s45, 0, s19
	s_abs_i32 s44, s27
	s_ashr_i32 s43, s27, 31
	v_mul_f32_e32 v12, 0x4f7ffffe, v12
	v_cvt_u32_f32_e32 v12, v12
	v_mov_b32_e32 v16, 0
	v_mov_b32_e32 v14, 0
	v_mov_b32_e32 v15, 0
	v_readfirstlane_b32 s47, v12
	s_mul_i32 s45, s45, s47
	s_mul_hi_u32 s45, s47, s45
	s_add_i32 s47, s47, s45
	s_mul_hi_u32 s45, s44, s47
	s_mul_i32 s47, s45, s19
	s_sub_i32 s44, s44, s47
	s_add_i32 s48, s45, 1
	s_sub_i32 s47, s44, s19
	s_cmp_ge_u32 s44, s19
	s_cselect_b32 s45, s48, s45
	s_cselect_b32 s44, s47, s44
	s_add_i32 s47, s45, 1
	s_cmp_ge_u32 s44, s19
	s_cselect_b32 s44, s47, s45
	s_xor_b32 s44, s44, s43
	s_sub_i32 s43, s44, s43
	s_mul_i32 s19, s43, s19
	s_sub_i32 s19, s27, s19
	s_lshl_b32 s44, s19, 4
	s_and_b32 s44, s44, 0xffffff80
	v_and_or_b32 v13, s19, 4, v104
	v_lshl_or_b32 v12, s19, 5, v103
	v_add_u32_e32 v13, s44, v13
	v_and_or_b32 v13, v12, s49, v13
	v_cndmask_b32_e64 v64, v12, v13, s[6:7]
	v_cmp_lt_i32_e32 vcc, -1, v64
	v_lshl_or_b32 v99, s43, 6, v102
	v_lshlrev_b64 v[100:101], 2, v[64:65]
	v_mov_b32_e32 v12, 0
	v_mov_b32_e32 v13, 0
	v_mov_b32_e32 v20, 0
	v_mov_b32_e32 v21, 0
	v_mov_b32_e32 v22, 0
	v_mov_b32_e32 v23, 0
	s_and_saveexec_b64 s[6:7], vcc
	s_cbranch_execz .LBB0_2209
	v_mad_i64_i32 v[12:13], s[44:45], s34, v99, 0
	v_or_b32_e32 v14, 8, v99
	v_lshl_add_u64 v[12:13], v[12:13], 2, s[28:29]
	v_mad_i64_i32 v[14:15], s[44:45], s34, v14, 0
	v_lshl_add_u64 v[12:13], v[12:13], 0, v[100:101]
	v_lshl_add_u64 v[14:15], v[14:15], 2, s[28:29]
	v_lshl_add_u64 v[18:19], v[14:15], 0, v[100:101]
	global_load_dwordx4 v[12:15], v[12:13], off nt
	s_nop 0
	global_load_dwordx4 v[20:23], v[18:19], off nt
.LBB0_2209:
	s_or_b64 exec, exec, s[6:7]
	v_mov_b32_e32 v17, 0
	v_mov_b32_e32 v18, 0
	v_mov_b32_e32 v19, 0
	v_mov_b32_e32 v32, 0
	v_mov_b32_e32 v33, 0
	v_mov_b32_e32 v34, 0
	v_mov_b32_e32 v35, 0
	s_and_saveexec_b64 s[6:7], vcc
	s_cbranch_execz .LBB0_2211
	v_or_b32_e32 v16, 16, v99
	v_or_b32_e32 v18, 24, v99
	v_mad_i64_i32 v[16:17], s[44:45], s34, v16, 0
	v_mad_i64_i32 v[18:19], s[44:45], s34, v18, 0
	v_lshl_add_u64 v[16:17], v[16:17], 2, s[28:29]
	v_lshl_add_u64 v[18:19], v[18:19], 2, s[28:29]
	v_lshl_add_u64 v[16:17], v[16:17], 0, v[100:101]
	v_lshl_add_u64 v[32:33], v[18:19], 0, v[100:101]
	global_load_dwordx4 v[16:19], v[16:17], off nt
	s_nop 0
	global_load_dwordx4 v[32:35], v[32:33], off nt
.LBB0_2211:
	s_or_b64 exec, exec, s[6:7]
	v_mov_b32_e32 v47, 0
	v_mov_b32_e32 v52, 0
	v_mov_b32_e32 v53, 0
	v_mov_b32_e32 v54, 0
	v_mov_b32_e32 v55, 0
	v_mov_b32_e32 v48, 0
	v_mov_b32_e32 v49, 0
	v_mov_b32_e32 v50, 0
	v_mov_b32_e32 v51, 0
	s_and_saveexec_b64 s[6:7], vcc
	s_cbranch_execz .LBB0_2213
	v_or_b32_e32 v44, 32, v99
	v_or_b32_e32 v46, 40, v99
	v_mad_i64_i32 v[44:45], s[44:45], s34, v44, 0
	v_mad_i64_i32 v[48:49], s[44:45], s34, v46, 0
	v_lshl_add_u64 v[44:45], v[44:45], 2, s[28:29]
	v_lshl_add_u64 v[48:49], v[48:49], 2, s[28:29]
	v_lshl_add_u64 v[44:45], v[44:45], 0, v[100:101]
	v_lshl_add_u64 v[48:49], v[48:49], 0, v[100:101]
	global_load_dwordx4 v[52:55], v[44:45], off nt
	s_nop 0
	global_load_dwordx4 v[48:51], v[48:49], off nt
.LBB0_2213:
	s_or_b64 exec, exec, s[6:7]
	v_mov_b32_e32 v46, 0
	v_mov_b32_e32 v45, 0
	v_mov_b32_e32 v44, 0
	v_mov_b32_e32 v63, 0
	v_mov_b32_e32 v62, 0
	v_mov_b32_e32 v61, 0
	v_mov_b32_e32 v60, 0
	s_and_saveexec_b64 s[6:7], vcc
	s_cbranch_execz .LBB0_2215
	v_or_b32_e32 v44, 48, v99
	v_or_b32_e32 v46, 56, v99
	v_mad_i64_i32 v[44:45], s[44:45], s34, v44, 0
	v_mad_i64_i32 v[46:47], s[44:45], s34, v46, 0
	v_lshl_add_u64 v[44:45], v[44:45], 2, s[28:29]
	v_lshl_add_u64 v[46:47], v[46:47], 2, s[28:29]
	v_lshl_add_u64 v[44:45], v[44:45], 0, v[100:101]
	v_lshl_add_u64 v[46:47], v[46:47], 0, v[100:101]
	global_load_dwordx4 v[60:63], v[44:45], off nt
	s_nop 0
	global_load_dwordx4 v[44:47], v[46:47], off nt

.LBB0_2249:
	v_cmp_gt_i32_e32 vcc, 0, v64
	s_and_saveexec_b64 s[18:19], vcc
	s_xor_b64 s[18:19], exec, s[18:19]
	s_or_saveexec_b64 s[18:19], s[18:19]
	s_lshl_b32 s20, s17, 6
	v_or_b32_e32 v100, s20, v104
	v_mov_b32_e32 v68, 0
	v_lshlrev_b64 v[102:103], 2, v[64:65]
	v_mov_b32_e32 v69, 0
	v_mov_b32_e32 v70, 0
	v_mov_b32_e32 v71, 0
	v_mov_b32_e32 v72, 0
	v_mov_b32_e32 v73, 0
	v_mov_b32_e32 v74, 0
	v_mov_b32_e32 v75, 0
	s_xor_b64 exec, exec, s[18:19]
	s_cbranch_execz .LBB0_2251
	v_or_b32_e32 v64, 8, v100
	v_mad_i64_i32 v[66:67], s[22:23], s16, v100, 0
	v_mad_i64_i32 v[68:69], s[22:23], s16, v64, 0
	v_lshl_add_u64 v[66:67], v[66:67], 2, s[14:15]
	v_lshl_add_u64 v[68:69], v[68:69], 2, s[14:15]
	v_lshl_add_u64 v[66:67], v[66:67], 0, v[102:103]
	v_lshl_add_u64 v[72:73], v[68:69], 0, v[102:103]
	global_load_dwordx4 v[68:71], v[66:67], off nt
	s_nop 0
	global_load_dwordx4 v[72:75], v[72:73], off nt
.LBB0_2251:
	s_or_b64 exec, exec, s[18:19]
	s_and_saveexec_b64 s[18:19], vcc
	s_xor_b64 s[18:19], exec, s[18:19]
	s_or_saveexec_b64 s[18:19], s[18:19]
	v_mov_b32_e32 v76, 0
	v_mov_b32_e32 v77, 0
	v_mov_b32_e32 v78, 0
	v_mov_b32_e32 v79, 0
	v_mov_b32_e32 v80, 0
	v_mov_b32_e32 v81, 0
	v_mov_b32_e32 v82, 0
	v_mov_b32_e32 v83, 0
	s_xor_b64 exec, exec, s[18:19]
	s_cbranch_execz .LBB0_2253
	v_or_b32_e32 v64, 16, v100
	v_mad_i64_i32 v[66:67], s[22:23], s16, v64, 0
	v_or_b32_e32 v64, 24, v100
	v_mad_i64_i32 v[76:77], s[22:23], s16, v64, 0
	v_lshl_add_u64 v[66:67], v[66:67], 2, s[14:15]
	v_lshl_add_u64 v[76:77], v[76:77], 2, s[14:15]
	v_lshl_add_u64 v[66:67], v[66:67], 0, v[102:103]
	v_lshl_add_u64 v[80:81], v[76:77], 0, v[102:103]
	global_load_dwordx4 v[76:79], v[66:67], off nt
	s_nop 0
	global_load_dwordx4 v[80:83], v[80:81], off nt
.LBB0_2253:
	s_or_b64 exec, exec, s[18:19]
	s_and_saveexec_b64 s[18:19], vcc
	s_xor_b64 s[18:19], exec, s[18:19]
	s_or_saveexec_b64 s[18:19], s[18:19]
	v_mov_b32_e32 v88, 0
	v_mov_b32_e32 v89, 0
	v_mov_b32_e32 v90, 0
	v_mov_b32_e32 v91, 0
	v_mov_b32_e32 v84, 0
	v_mov_b32_e32 v85, 0
	v_mov_b32_e32 v86, 0
	v_mov_b32_e32 v87, 0
	s_xor_b64 exec, exec, s[18:19]
	s_cbranch_execz .LBB0_2255
	v_or_b32_e32 v64, 32, v100
	v_mad_i64_i32 v[66:67], s[22:23], s16, v64, 0
	v_or_b32_e32 v64, 40, v100
	v_mad_i64_i32 v[84:85], s[22:23], s16, v64, 0
	v_lshl_add_u64 v[66:67], v[66:67], 2, s[14:15]
	v_lshl_add_u64 v[84:85], v[84:85], 2, s[14:15]
	v_lshl_add_u64 v[66:67], v[66:67], 0, v[102:103]
	v_lshl_add_u64 v[84:85], v[84:85], 0, v[102:103]
	global_load_dwordx4 v[88:91], v[66:67], off nt
	s_nop 0
	global_load_dwordx4 v[84:87], v[84:85], off nt
.LBB0_2255:
	s_or_b64 exec, exec, s[18:19]
	s_and_saveexec_b64 s[18:19], vcc
	s_xor_b64 s[18:19], exec, s[18:19]
	s_or_saveexec_b64 s[18:19], s[18:19]
	v_mov_b32_e32 v66, v65
	v_mov_b32_e32 v67, v65
	v_mov_b32_e32 v64, v65
	v_mov_b64_e32 v[98:99], v[66:67]
	v_mov_b32_e32 v92, 0
	v_mov_b64_e32 v[96:97], v[64:65]
	v_mov_b32_e32 v93, 0
	v_mov_b32_e32 v94, 0
	v_mov_b32_e32 v95, 0
	s_xor_b64 exec, exec, s[18:19]
	s_cbranch_execz .LBB0_2259
	v_or_b32_e32 v64, 48, v100
	v_mad_i64_i32 v[66:67], s[22:23], s16, v64, 0
	v_or_b32_e32 v64, 56, v100
	v_mad_i64_i32 v[92:93], s[16:17], s16, v64, 0
	v_lshl_add_u64 v[66:67], v[66:67], 2, s[14:15]
	v_lshl_add_u64 v[92:93], v[92:93], 2, s[14:15]
	v_lshl_add_u64 v[66:67], v[66:67], 0, v[102:103]
	v_lshl_add_u64 v[96:97], v[92:93], 0, v[102:103]
	global_load_dwordx4 v[92:95], v[66:67], off nt
	s_nop 0
	global_load_dwordx4 v[96:99], v[96:97], off nt

.LBB0_2283:
	v_mov_b32_e32 v2, v65
	v_mov_b32_e32 v3, v65
	v_mov_b32_e32 v0, v65
	v_mov_b32_e32 v1, v65
	v_mov_b64_e32 v[6:7], v[2:3]
	v_cmp_lt_i32_e32 vcc, -1, v64
	v_lshl_or_b32 v66, s23, 6, v104
	v_mov_b32_e32 v16, 0
	v_mov_b64_e32 v[4:5], v[0:1]
	v_mov_b32_e32 v20, 0
	v_mov_b32_e32 v21, 0
	v_mov_b32_e32 v22, 0
	v_mov_b32_e32 v23, 0
	s_and_saveexec_b64 s[26:27], vcc
	s_cbranch_execz .LBB0_2285
	v_or_b32_e32 v17, 8, v66
	v_mad_i64_i32 v[4:5], s[34:35], s22, v66, 0
	v_mad_i64_i32 v[18:19], s[34:35], s22, v17, 0
	v_lshl_add_u64 v[4:5], v[4:5], 2, s[16:17]
	v_lshlrev_b64 v[6:7], 2, v[64:65]
	v_lshl_add_u64 v[18:19], v[18:19], 2, s[16:17]
	v_lshl_add_u64 v[4:5], v[4:5], 0, v[6:7]
	v_lshl_add_u64 v[6:7], v[18:19], 0, v[6:7]
	global_load_dwordx4 v[20:23], v[4:5], off nt
	s_nop 0
	global_load_dwordx4 v[4:7], v[6:7], off nt
.LBB0_2285:
	s_or_b64 exec, exec, s[26:27]
	v_mov_b32_e32 v17, 0
	v_mov_b32_e32 v18, 0
	v_mov_b32_e32 v19, 0
	s_and_saveexec_b64 s[26:27], vcc
	s_cbranch_execz .LBB0_2287
	v_or_b32_e32 v0, 16, v66
	v_or_b32_e32 v16, 24, v66
	v_mad_i64_i32 v[0:1], s[34:35], s22, v0, 0
	v_mad_i64_i32 v[16:17], s[34:35], s22, v16, 0
	v_lshl_add_u64 v[0:1], v[0:1], 2, s[16:17]
	v_lshlrev_b64 v[2:3], 2, v[64:65]
	v_lshl_add_u64 v[16:17], v[16:17], 2, s[16:17]
	v_lshl_add_u64 v[0:1], v[0:1], 0, v[2:3]
	v_lshl_add_u64 v[2:3], v[16:17], 0, v[2:3]
	global_load_dwordx4 v[16:19], v[0:1], off nt
	s_nop 0
	global_load_dwordx4 v[0:3], v[2:3], off nt
.LBB0_2287:
	s_or_b64 exec, exec, s[26:27]
	v_mov_b32_e32 v32, v65
	v_mov_b32_e32 v33, v65
	v_mov_b32_e32 v34, v65
	v_mov_b32_e32 v35, v65
	v_mov_b32_e32 v39, 0
	v_mov_b32_e32 v44, 0
	v_mov_b32_e32 v45, 0
	v_mov_b32_e32 v46, 0
	v_mov_b32_e32 v47, 0
	s_and_saveexec_b64 s[26:27], vcc
	s_cbranch_execz .LBB0_2289
	v_or_b32_e32 v32, 32, v66
	v_or_b32_e32 v36, 40, v66
	v_mad_i64_i32 v[32:33], s[34:35], s22, v32, 0
	v_mad_i64_i32 v[36:37], s[34:35], s22, v36, 0
	v_lshl_add_u64 v[32:33], v[32:33], 2, s[16:17]
	v_lshlrev_b64 v[34:35], 2, v[64:65]
	v_lshl_add_u64 v[36:37], v[36:37], 2, s[16:17]
	v_lshl_add_u64 v[32:33], v[32:33], 0, v[34:35]
	v_lshl_add_u64 v[34:35], v[36:37], 0, v[34:35]
	global_load_dwordx4 v[44:47], v[32:33], off nt
	s_nop 0
	global_load_dwordx4 v[32:35], v[34:35], off nt
.LBB0_2289:
	s_or_b64 exec, exec, s[26:27]
	v_mov_b32_e32 v38, 0
	v_mov_b32_e32 v37, 0
	v_mov_b32_e32 v36, 0
	v_mov_b32_e32 v59, 0
	v_mov_b32_e32 v58, 0
	v_mov_b32_e32 v57, 0
	v_mov_b32_e32 v56, 0
	s_and_saveexec_b64 s[26:27], vcc
	s_cbranch_execz .LBB0_2291
	v_or_b32_e32 v36, 48, v66
	v_or_b32_e32 v56, 56, v66
	v_mad_i64_i32 v[36:37], s[34:35], s22, v36, 0
	v_mad_i64_i32 v[56:57], s[22:23], s22, v56, 0
	v_lshl_add_u64 v[36:37], v[36:37], 2, s[16:17]
	v_lshlrev_b64 v[38:39], 2, v[64:65]
	v_lshl_add_u64 v[56:57], v[56:57], 2, s[16:17]
	v_lshl_add_u64 v[36:37], v[36:37], 0, v[38:39]
	v_lshl_add_u64 v[38:39], v[56:57], 0, v[38:39]
	global_load_dwordx4 v[56:59], v[36:37], off nt
	s_nop 0
	global_load_dwordx4 v[36:39], v[38:39], off nt

.LBB0_2316:
	v_mov_b32_e32 v10, v65
	v_mov_b32_e32 v11, v65
	v_mov_b32_e32 v8, v65
	v_mov_b32_e32 v9, v65
	s_waitcnt vmcnt(0)
	v_mov_b64_e32 v[14:15], v[10:11]
	v_cmp_lt_i32_e32 vcc, -1, v64
	v_lshl_or_b32 v66, s21, 6, v104
	v_mov_b32_e32 v28, 0
	v_mov_b64_e32 v[12:13], v[8:9]
	v_mov_b32_e32 v24, 0
	v_mov_b32_e32 v25, 0
	v_mov_b32_e32 v26, 0
	v_mov_b32_e32 v27, 0
	s_and_saveexec_b64 s[26:27], vcc
	s_cbranch_execz .LBB0_2318
	v_or_b32_e32 v24, 8, v66
	v_mad_i64_i32 v[12:13], s[44:45], s40, v66, 0
	v_mad_i64_i32 v[24:25], s[44:45], s40, v24, 0
	v_lshl_add_u64 v[12:13], v[12:13], 2, s[36:37]
	v_lshlrev_b64 v[14:15], 2, v[64:65]
	v_lshl_add_u64 v[24:25], v[24:25], 2, s[36:37]
	v_lshl_add_u64 v[12:13], v[12:13], 0, v[14:15]
	v_lshl_add_u64 v[14:15], v[24:25], 0, v[14:15]
	global_load_dwordx4 v[24:27], v[12:13], off nt
	s_nop 0
	global_load_dwordx4 v[12:15], v[14:15], off nt
.LBB0_2318:
	s_or_b64 exec, exec, s[26:27]
	v_mov_b32_e32 v29, 0
	v_mov_b32_e32 v30, 0
	v_mov_b32_e32 v31, 0
	s_and_saveexec_b64 s[26:27], vcc
	s_cbranch_execz .LBB0_2320
	v_or_b32_e32 v8, 16, v66
	v_or_b32_e32 v28, 24, v66
	v_mad_i64_i32 v[8:9], s[44:45], s40, v8, 0
	v_mad_i64_i32 v[28:29], s[44:45], s40, v28, 0
	v_lshl_add_u64 v[8:9], v[8:9], 2, s[36:37]
	v_lshlrev_b64 v[10:11], 2, v[64:65]
	v_lshl_add_u64 v[28:29], v[28:29], 2, s[36:37]
	v_lshl_add_u64 v[8:9], v[8:9], 0, v[10:11]
	v_lshl_add_u64 v[10:11], v[28:29], 0, v[10:11]
	global_load_dwordx4 v[28:31], v[8:9], off nt
	s_nop 0
	global_load_dwordx4 v[8:11], v[10:11], off nt
.LBB0_2320:
	s_or_b64 exec, exec, s[26:27]
	v_mov_b32_e32 v40, v65
	v_mov_b32_e32 v41, v65
	v_mov_b32_e32 v42, v65
	v_mov_b32_e32 v43, v65
	v_mov_b32_e32 v51, 0
	v_mov_b32_e32 v52, 0
	v_mov_b32_e32 v53, 0
	v_mov_b32_e32 v54, 0
	v_mov_b32_e32 v55, 0
	s_and_saveexec_b64 s[26:27], vcc
	s_cbranch_execz .LBB0_2322
	v_or_b32_e32 v40, 32, v66
	v_or_b32_e32 v48, 40, v66
	v_mad_i64_i32 v[40:41], s[44:45], s40, v40, 0
	v_mad_i64_i32 v[48:49], s[44:45], s40, v48, 0
	v_lshl_add_u64 v[40:41], v[40:41], 2, s[36:37]
	v_lshlrev_b64 v[42:43], 2, v[64:65]
	v_lshl_add_u64 v[48:49], v[48:49], 2, s[36:37]
	v_lshl_add_u64 v[40:41], v[40:41], 0, v[42:43]
	v_lshl_add_u64 v[42:43], v[48:49], 0, v[42:43]
	global_load_dwordx4 v[52:55], v[40:41], off nt
	s_nop 0
	global_load_dwordx4 v[40:43], v[42:43], off nt
.LBB0_2322:
	s_or_b64 exec, exec, s[26:27]
	v_mov_b32_e32 v50, 0
	v_mov_b32_e32 v49, 0
	v_mov_b32_e32 v48, 0
	v_mov_b32_e32 v63, 0
	v_mov_b32_e32 v62, 0
	v_mov_b32_e32 v61, 0
	v_mov_b32_e32 v60, 0
	s_and_saveexec_b64 s[26:27], vcc
	s_cbranch_execz .LBB0_2324
	v_or_b32_e32 v48, 48, v66
	v_or_b32_e32 v60, 56, v66
	v_mad_i64_i32 v[48:49], s[44:45], s40, v48, 0
	v_mad_i64_i32 v[60:61], s[40:41], s40, v60, 0
	v_lshl_add_u64 v[48:49], v[48:49], 2, s[36:37]
	v_lshlrev_b64 v[50:51], 2, v[64:65]
	v_lshl_add_u64 v[60:61], v[60:61], 2, s[36:37]
	v_lshl_add_u64 v[48:49], v[48:49], 0, v[50:51]
	v_lshl_add_u64 v[50:51], v[60:61], 0, v[50:51]
	global_load_dwordx4 v[60:63], v[48:49], off nt
	s_nop 0
	global_load_dwordx4 v[48:51], v[50:51], off nt
